# additionally XCC-local barrier at the P2-P3 seam (SSM-branch Z moved to the unused gate region so P3 may overlap other XCCs attention)
# baseline (speedup 1.0000x reference)
; __device__ __forceinline__ void attn_item(const Args& a, LAS unsigned char* lds, int item, int wave, int lane) {
;     ...
;     const int r = wave >> 1, qh = wave & 1, hq = kvh * 4 + r, ql = lane & 31, hi = lane >> 5;
;     const float sink = a.in[6][hq];
;     const float* qnw = a.in[4];
;     const float L2E = 1.4426950408889634f;
;     for (int q4 = 0; q4 < 4; ++q4) {
;         const int bl = q4 >> 1, qb = q4 & 1, blk = blk0 + bl;
;         const int qblk = 2 * qh + qb;
;         const size_t qrow = (size_t)b * SEQ + blk * 128 + qblk * 32 + ql;
;         bf16x8 qf[4];
;         {
;             u32x4 qw[4]; float ss = 0.f;
; #pragma unroll
;             for (int ks = 0; ks < 4; ++ks) { qw[ks] = *(const u32x4*)(QB + qrow * DM + hq * 64 + 16 * ks + 8 * hi);
;                 const unsigned ww[4] = {qw[ks].x, qw[ks].y, qw[ks].z, qw[ks].w};
; #pragma unroll
;                 for (int e = 0; e < 4; ++e) { const float lo = bf_lo(ww[e]), h2 = bf_hi(ww[e]); ss += lo * lo + h2 * h2; } }
;             ss += __shfl_xor(ss, 32);
;             const float rs = __builtin_amdgcn_rsqf(ss * (1.0f / 64.0f) + EPS) * 0.125f;
; #pragma unroll
;             for (int ks = 0; ks < 4; ++ks) { const f32x4 g0 = *(const f32x4*)(qnw + 16 * ks + 8 * hi), g1 = *(const f32x4*)(qnw + 16 * ks + 8 * hi + 4);
;                 u32x4 o; o.x = cvt_pk(bf_lo(qw[ks].x) * rs * g0.x, bf_hi(qw[ks].x) * rs * g0.y); o.y = cvt_pk(bf_lo(qw[ks].y) * rs * g0.z, bf_hi(qw[ks].y) * rs * g0.w);
;                 o.z = cvt_pk(bf_lo(qw[ks].z) * rs * g1.x, bf_hi(qw[ks].z) * rs * g1.y); o.w = cvt_pk(bf_lo(qw[ks].w) * rs * g1.z, bf_hi(qw[ks].w) * rs * g1.w);
;                 qf[ks] = __builtin_bit_cast(bf16x8, o); }
;         }
;         f32x16 S[6];
; #pragma unroll
;         for (int i = 0; i < 6; ++i) {
;             const int kb = (i == 0) ? 0 : 4 * bl + qblk + i;
;             f32x16 acc;
; #pragma unroll
;             for (int e = 0; e < 16; ++e) acc[e] = 0.f;
; #pragma unroll
;             for (int ks = 0; ks < 4; ++ks) { const bf16x8 kf = *(const LAS bf16x8*)(lds + ATT_K_OFF + (kb * 32 + ql) * KP + (16 * ks + 8 * hi) * 2);
;                 acc = __builtin_amdgcn_mfma_f32_32x32x16_bf16(kf, qf[ks], acc, 0, 0, 0); }
;             S[i] = acc;
;         }
;         const float NEG = -INFINITY;
; #pragma unroll
;         for (int e = 0; e < 16; ++e) { const int kr = crow(e, hi);
.LBB0_245:
	s_or_b64 exec, exec, s[0:1]
	v_mov_b32_e32 v0, 0x23f30
	ds_read_b64 v[0:1], v0
	s_waitcnt lgkmcnt(0)
	v_readfirstlane_b32 s100, v0
	v_readfirstlane_b32 s101, v1
	s_nop 3
	s_cmp_eq_u32 s101, 1
	s_cbranch_scc0 .Lxb_norelabel
	s_lshl_b32 s100, s100, 3
	s_or_b32 s2, s100, s3
	s_lshl_b32 s40, s2, 3
.Lxb_norelabel:
	s_add_u32 s60, s58, 0x60000
	s_addc_u32 s61, s59, 0
	s_cmpk_lt_i32 s2, 0x200
	s_cselect_b64 s[54:55], -1, 0
	s_cmpk_gt_i32 s2, 0x1ff
	v_lshrrev_b32_e32 v105, 5, v128
	v_cmp_gt_u32_e64 s[0:1], 32, v128
	v_or_b32_e32 v104, 32, v128
	s_waitcnt lgkmcnt(0)
	s_barrier
	s_cbranch_scc1 .LBB0_261
	v_mbcnt_hi_u32_b32 v2, -1, v235
	v_and_b32_e32 v1, 64, v2
	v_xor_b32_e32 v0, 1, v2
	v_add_u32_e32 v3, 64, v1
	v_cmp_lt_i32_e32 vcc, v0, v3
	v_mov_b32_e32 v99, 0
	v_mov_b32_e32 v1, v99
	v_cndmask_b32_e32 v0, v2, v0, vcc
	v_lshlrev_b32_e32 v113, 2, v0
	v_xor_b32_e32 v0, 2, v2
	v_cmp_lt_i32_e32 vcc, v0, v3
	v_lshlrev_b32_e32 v96, 4, v131
	v_mov_b32_e32 v97, v99
	v_cndmask_b32_e32 v0, v2, v0, vcc
	v_lshlrev_b32_e32 v124, 2, v0
	v_xor_b32_e32 v0, 4, v2
	v_cmp_lt_i32_e32 vcc, v0, v3
	v_lshlrev_b32_e32 v98, 5, v131
	v_lshl_add_u64 v[100:101], s[4:5], 0, v[96:97]
	v_cndmask_b32_e32 v0, v2, v0, vcc
	v_lshlrev_b32_e32 v125, 2, v0
	v_lshlrev_b32_e32 v0, 4, v105
	v_lshl_add_u64 v[108:109], s[48:49], 0, v[0:1]
	v_xor_b32_e32 v1, 32, v2
	v_cmp_lt_i32_e32 vcc, v1, v3
	v_lshl_add_u64 v[106:107], s[86:87], 0, v[98:99]
	s_lshl_b32 s4, s33, 1
	v_lshlrev_b32_e32 v98, 3, v105
	v_cndmask_b32_e32 v1, v2, v1, vcc
	v_and_b32_e32 v2, 32, v128
	v_mov_b32_e32 v3, v99
	v_lshl_add_u64 v[102:103], s[6:7], 0, v[96:97]
	s_and_b32 s65, s4, 2
	v_lshlrev_b32_e32 v97, 2, v1
	v_lshl_add_u64 v[110:111], s[84:85], 0, v[2:3]
	v_add_u32_e32 v112, 0, v0
	v_lshlrev_b32_e32 v2, 2, v105
	v_lshl_add_u64 v[0:1], s[58:59], 0, v[98:99]
	s_mov_b64 s[4:5], 0x19400000
	v_lshl_add_u64 v[114:115], v[0:1], 0, s[4:5]
	v_or_b32_e32 v1, 2, v2
	v_cmp_gt_u32_e64 s[8:9], v1, v130
	v_or_b32_e32 v1, 3, v2
	v_cmp_gt_u32_e64 s[10:11], v1, v130
	v_or_b32_e32 v1, 8, v2
	v_cmp_gt_u32_e64 s[12:13], v1, v130
	v_or_b32_e32 v1, 9, v2
	v_cmp_gt_u32_e64 s[14:15], v1, v130
	v_or_b32_e32 v1, 10, v2
	v_cmp_gt_u32_e64 s[16:17], v1, v130
	v_or_b32_e32 v1, 11, v2
	v_cmp_gt_u32_e64 s[18:19], v1, v130
	v_or_b32_e32 v1, 16, v2
	v_cmp_gt_u32_e64 s[20:21], v1, v130
	v_or_b32_e32 v1, 17, v2
	v_cmp_gt_u32_e64 s[22:23], v1, v130
	v_or_b32_e32 v1, 18, v2
	v_cmp_gt_u32_e64 s[24:25], v1, v130
	v_or_b32_e32 v1, 19, v2
	v_cmp_gt_u32_e64 s[26:27], v1, v130
	v_or_b32_e32 v1, 24, v2
	v_cmp_gt_u32_e64 s[28:29], v1, v130
	v_or_b32_e32 v1, 25, v2
	v_cmp_gt_u32_e64 s[30:31], v1, v130
	v_or_b32_e32 v1, 26, v2
	s_lshr_b32 s41, s41, 7
	v_cmp_gt_u32_e64 s[34:35], v1, v130
	v_or_b32_e32 v1, 27, v2
	v_mul_u32_u24_e32 v4, 0x1a30, v131
	v_sub_u32_e32 v3, v112, v98
	s_movk_i32 s76, 0x90
	v_mul_u32_u24_e32 v0, 0x90, v130
	v_cmp_gt_u32_e64 s[36:37], v1, v130
	s_cmp_eq_u32 s65, 0
	s_movk_i32 s42, 0x348
	v_lshlrev_b32_e32 v1, 1, v141
	s_mov_b32 s63, 0
	v_cmp_gt_u32_e64 s[4:5], v2, v130
	v_cmp_lt_u32_e64 s[6:7], v2, v130
	s_cselect_b64 s[38:39], -1, 0
	v_mad_u32_u24 v126, v130, s42, v3
	v_mad_u32_u24 v127, v104, s42, v3
	v_or_b32_e32 v132, 0x8000, v141
	v_add3_u32 v133, v4, v1, 0
	v_mad_u32_u24 v134, v141, s76, 0
	s_lshl_b32 s77, s2, 1
	s_lshl_b32 s78, s92, 1
	s_movk_i32 s79, 0x7f
	s_movk_i32 s80, 0x100
	s_movk_i32 s81, 0x500
	v_mov_b32_e32 v135, 0x358637bd
	s_movk_i32 s82, 0xaff
	s_mov_b32 s64, 0x3fb8aa3b
	v_add_u32_e32 v136, v112, v0
	s_mov_b32 s83, 0xff800000
	v_mov_b32_e32 v137, 0xff800000
	s_mov_b32 s84, s2
	s_branch .LBB0_248

; __device__ __forceinline__ unsigned xb_ld(unsigned* p)              { return __hip_atomic_load(p, __ATOMIC_RELAXED, __HIP_MEMORY_SCOPE_AGENT); }
; __device__ __forceinline__ unsigned xb_add(unsigned* p, unsigned v) { return __hip_atomic_fetch_add(p, v, __ATOMIC_RELAXED, __HIP_MEMORY_SCOPE_AGENT); }
; #define XB_SPIN(cond, bar) do { unsigned _sp = 0; while (cond) { __builtin_amdgcn_s_sleep(1); \
;     if ((++_sp & 255u) == 0u) { if (xb_ld(&(bar)[XB_TMO])) break; if (_sp > XB_SPIN_CAP) { atomicAdd(&(bar)[XB_TMO], 1u); break; } } } } while (0)
; __device__ __forceinline__ void xcd_barrier(const XcdBarrier& b) {
;     ...
;         const unsigned old = xb_add(&bar[XB_XSUB(b.x)], 1u);
;         const unsigned gen = old / nloc;
;         if (old + 1u == (gen + 1u) * nloc) {
;             __builtin_amdgcn_fence(__ATOMIC_RELEASE, "agent");
;             asm volatile("s_waitcnt vmcnt(0)" ::: "memory");
;             const unsigned og = xb_add(&bar[XB_TOP], 1u);
;             const unsigned tg = og / nx;
;             if (og + 1u == (tg + 1u) * nx) xb_add(&bar[XB_TOPGEN], 1u);
;             else XB_SPIN(xb_ld(&bar[XB_TOPGEN]) == tg, bar);
;             __builtin_amdgcn_fence(__ATOMIC_ACQUIRE, "agent");
;             xb_add(&bar[XB_XGEN(b.x)], 1u);
;             asm volatile("s_waitcnt vmcnt(0)" ::: "memory");
.LBB0_306:
	s_andn2_saveexec_b64 s[6:7], s[6:7]
	s_cbranch_execz .LBB0_326
	s_mov_b64 s[6:7], exec
	s_cmp_eq_u32 s101, 1
	s_cbranch_scc1 .LBB0_323
	buffer_wbl2 sc1
	s_waitcnt lgkmcnt(0)
	s_waitcnt vmcnt(0)
	v_mbcnt_lo_u32_b32 v1, s6, 0
	v_mbcnt_hi_u32_b32 v1, s7, v1
	v_cmp_eq_u32_e32 vcc, 0, v1
	s_and_saveexec_b64 s[8:9], vcc
	s_cbranch_execz .LBB0_309
	s_bcnt1_i32_b64 s6, s[6:7]
	v_mov_b32_e32 v2, 0xc3000
	v_mov_b32_e32 v3, s6
	global_atomic_add v2, v2, v3, s[58:59] offset:1024 sc0

; template <bool FINAL>
; __device__ __forceinline__ void ssm_item(const Args& a, LAS unsigned char* lds, int item, int wave, int lane) {
;     ...
;     const bf16* U = (const bf16*)(ws + WS_U); bf16* Z = (bf16*)(ws + WS_Q);
;     float* E = (float*)(ws + WS_E);
;     const bool meta = (!FINAL) && item >= 256;
;     const int oct = item & 7, cp = (item >> 3) & 15, bp = (item >> 7) & 1;
;     const int g = oct * 8 + wave, j = lane & 31, hi = lane >> 5;
;     const int b0 = bp * 2, c0 = 2 * cp;
;     bf16x8 bbf[4];
; #pragma unroll
;     for (int k = 0; k < 4; ++k) bbf[k] = *(const bf16x8*)((const bf16*)(ws + WS_BB) + ((size_t)g * 128 + k * 32 + j) * 16 + 8 * hi);
;     const f32x2 a0 = ((const f32x2*)(ws + WS_ATAB))[g * 64 + j], a1 = ((const f32x2*)(ws + WS_ATAB))[g * 64 + 32 + j];
;     const f32x2 a0x = (f32x2){a0.x, a0.x}, a0y = (f32x2){a0.y, a0.y}, na0y = (f32x2){-a0.y, -a0.y}, a1x = (f32x2){a1.x, a1.x}, a1y = (f32x2){a1.y, a1.y}, na1y = (f32x2){-a1.y, -a1.y};
;     f32x2 s0r = (f32x2){0.f, 0.f}, s0i = s0r, s1r = s0r, s1i = s0r;
;     bf16x8 cmf[4]; f32x4 dsk;
;     if (FINAL) {
; #pragma unroll
;         for (int k = 0; k < 4; ++k) cmf[k] = *(const bf16x8*)((const bf16*)(ws + WS_CM) + ((size_t)g * 16 + (lane & 15)) * 128 + 32 * k + 8 * (lane >> 4));
;         dsk = *(const f32x4*)(a.in[14] + g * 16 + 4 * (lane >> 4));
;         const f32x2 t0 = ((const f32x2*)(ws + WS_ATAB2))[g * 64 + j], t1 = ((const f32x2*)(ws + WS_ATAB2))[g * 64 + 32 + j];
;         const f32x2 m0 = ((const f32x2*)(ws + WS_SMETA))[g * 64 + j], m1 = ((const f32x2*)(ws + WS_SMETA))[g * 64 + 32 + j];
;         float c0r = m0.x, c0i = m0.y, c1r = m1.x, c1i = m1.y;
;         const f32x2* Eb = (const f32x2*)E + ((size_t)((b0 + hi) * 64 + g) * NCHUNK) * 64;
; #pragma unroll
;         for (int half = 0; half < 2; ++half) {
;             if (half * 16 < c0) {
;                 f32x2 e0[16], e1[16];
; #pragma unroll
;                 for (int c = 0; c < 16; ++c) { const int cc = half * 16 + c < NCHUNK - 1 ? half * 16 + c : NCHUNK - 2; e0[c] = Eb[cc * 64 + j]; e1[c] = Eb[cc * 64 + 32 + j]; }
; #pragma unroll
;                 for (int c = 0; c < 16; ++c) if (half * 16 + c < c0) {
;                     const float n0r = fmaf(t0.x, c0r, fmaf(-t0.y, c0i, e0[c].x)), n0i = fmaf(t0.x, c0i, fmaf(t0.y, c0r, e0[c].y));
.LBB0_338:
	s_lshl_b32 s21, s20, 7
	s_lshl_b32 s22, s20, 6
	s_and_b32 s21, s21, 0x4000
	s_and_b32 s24, s22, 0x1e00
	s_lshl_b32 s22, s40, 4
	v_or_b32_e32 v6, s21, v161
	s_and_b32 s22, s22, 0x380
	v_or_b32_e32 v6, s24, v6
	s_add_i32 s22, s14, s22
	v_lshlrev_b32_e32 v106, 11, v6
	s_lshl_b32 s22, s22, 1
	s_mov_b32 s23, s11
	s_or_b32 s21, s24, s21
	v_lshl_add_u64 v[6:7], v[106:107], 0, s[22:23]
	v_add_lshl_u32 v106, s21, v241, 11
	s_lshl_b32 s21, s13, 6
	v_or_b32_e32 v14, s21, v130
	v_lshl_add_u64 v[8:9], v[106:107], 0, s[22:23]
	v_lshlrev_b32_e32 v106, 3, v14
	v_or_b32_e32 v16, s21, v104
	v_lshl_add_u64 v[14:15], v[4:5], 0, v[106:107]
	v_lshlrev_b32_e32 v106, 3, v16
	v_lshl_add_u64 v[4:5], v[4:5], 0, v[106:107]
	global_load_dwordx2 v[206:207], v[14:15], off
	global_load_dwordx2 v[204:205], v[4:5], off
	v_or_b32_e32 v4, s12, v163
	v_or_b32_e32 v5, s13, v165
	v_lshlrev_b32_e32 v4, 13, v4
	v_lshlrev_b32_e32 v5, 8, v5
	v_or_b32_e32 v14, s13, v169
	v_or3_b32 v4, v4, v5, v167
	s_lshl_b32 s12, s12, 13
	v_lshlrev_b32_e32 v14, 8, v14
	v_lshlrev_b32_e32 v106, 11, v4
	v_or3_b32 v16, v14, s12, v131
	v_lshl_add_u64 v[4:5], s[52:53], 0, v[106:107]
	v_lshlrev_b32_e32 v106, 11, v16
	s_lshl_b32 s10, s10, 1
	v_lshl_add_u64 v[14:15], s[52:53], 0, v[106:107]
	v_lshl_add_u64 v[4:5], v[4:5], 0, s[10:11]
	v_mov_b32_e32 v189, v107
	v_lshl_add_u64 v[14:15], v[14:15], 0, s[10:11]
	v_mov_b32_e32 v191, v107
	v_lshl_add_u64 v[4:5], v[4:5], 0, v[188:189]
	v_lshl_add_u64 v[14:15], v[14:15], 0, v[190:191]
	global_load_dwordx4 v[100:103], v[4:5], off
	global_load_dwordx2 v[218:219], v[14:15], off
	v_add_co_u32_e32 v4, vcc, 0x1000000, v14
	v_xor_b32_e32 v202, 0x80000000, v195
	s_nop 0
	v_addc_co_u32_e32 v5, vcc, 0, v15, vcc
	global_load_dwordx2 v[212:213], v[4:5], off
	v_xor_b32_e32 v196, 0x80000000, v193
	v_mov_b32_e32 v200, v195
	v_mov_b32_e32 v201, v195
	v_mov_b32_e32 v198, v193
	v_mov_b32_e32 v199, v193
	v_mov_b32_e32 v195, v194
	v_mov_b32_e32 v193, v192
	s_waitcnt vmcnt(6)
	v_mov_b32_e32 v216, v10
	s_waitcnt vmcnt(5)
	v_mov_b32_e32 v214, v12
	v_mov_b32_e32 v203, v202
	v_mov_b32_e32 v197, v196
	v_lshl_add_u64 v[208:209], v[114:115], 0, v[6:7]
	v_lshl_add_u64 v[210:211], v[116:117], 0, v[8:9]
	v_lshlrev_b32_e32 v106, 10, v16
	s_mov_b64 s[12:13], 0
	s_waitcnt vmcnt(4)
	v_fma_f32 v217, -v3, v11, v206
	v_fmac_f32_e32 v207, v3, v10
	s_waitcnt vmcnt(3)
	v_fma_f32 v215, -v1, v13, v204
	v_fmac_f32_e32 v205, v1, v12
	v_fmac_f32_e32 v217, v2, v10
	v_fmac_f32_e32 v207, v2, v11
	v_fmac_f32_e32 v215, v0, v12
	v_fmac_f32_e32 v205, v0, v13
	v_mov_b32_e32 v206, v11
	v_mov_b32_e32 v204, v13
	v_subrev_u32_e32 v137, s58, v208
	v_subrev_u32_e32 v139, s58, v210
	s_add_u32 s76, s58, 0xd104000
	s_addc_u32 s77, s59, 0
	s_add_u32 s78, s58, 0xe104000
	s_addc_u32 s79, s59, 0
	s_add_u32 s66, s58, 0xd108000
	s_addc_u32 s67, s59, 0
	s_add_u32 s68, s58, 0xe108000
	s_addc_u32 s69, s59, 0
	s_add_u32 s70, s58, 0x11200000
	s_addc_u32 s71, s59, 0
	s_add_u32 s74, s58, 0x12200000
	s_addc_u32 s75, s59, 0
	global_load_dwordx4 v[248:251], v139, s[58:59]
	s_lshl_b32 s80, s33, 10
	s_add_i32 s80, s80, 0x11000
	v_and_b32_e32 v147, 63, v224
	v_and_b32_e32 v141, 31, v147
	v_lshlrev_b32_e32 v141, 5, v141
	v_lshrrev_b32_e32 v145, 5, v147
	v_lshl_or_b32 v141, v145, 4, v141
	v_add_u32_e32 v141, s80, v141
	v_and_b32_e32 v143, 6, v147
	v_lshlrev_b32_e32 v143, 2, v143
	v_and_b32_e32 v145, 1, v147
	v_lshl_or_b32 v143, v145, 1, v143
	v_bfe_u32 v145, v147, 3, 1
	v_or_b32_e32 v143, v143, v145
	v_lshlrev_b32_e32 v143, 5, v143
	v_lshrrev_b32_e32 v145, 5, v147
	v_lshl_or_b32 v143, v145, 4, v143
	v_bfe_u32 v145, v147, 4, 1
	v_lshl_or_b32 v143, v145, 3, v143
	v_add_u32_e32 v143, s80, v143
	s_mov_b32 s62, 0xbdd2d3e8
	s_mov_b32 s63, 0xbdd2d3e8
	s_mov_b32 s64, 0x3f800000
	s_mov_b32 s65, 0x3f800000
	v_mov_b32_e32 v246, 0xc0135761
	v_add_u32_e32 v245, 0x440, v242
	v_add_u32_e32 v247, 0x880, v242
	v_add_u32_e32 v106, 0xcc0, v242
	v_add_u32_e32 v139, 0x4000, v139
	s_mov_b32 s12, 0
	s_waitcnt vmcnt(0)

; template <class Epi, class Sched, bool ALIGN_EPI = false, bool SP2 = false, bool F16 = false>
; __device__ __forceinline__ void gemm_phase(PG8_LAS unsigned char* lds, const Gemm g, const Sched& S, const Epi& E) {
;     ...
;     Unit cur, nxt; int ui = 0;
;     if (!S.next(0, cur)) return;
; __global__ void __launch_bounds__(NTHREADS, 2) mk_fwd(Args a) {
;     ...
;     { pg8::Gemm g{(const pg8::bf16_t*)(ws + WS_Q), (const pg8::bf16_t*)(ws + WS_W2), NTOK, 2048, DM}; pg8::StaticOrder S; S.init(NTOK, 2048, G, c);
;       EpiGlu E{(bf16*)(ws + WS_U), DM, (float*)(ws + WS_ROWSB)};
;       pg8::gemm_phase<EpiGlu, pg8::StaticOrder, true, true>(lds, g, S, E); }
.LBB0_393:
	s_or_b64 exec, exec, s[0:1]
	s_add_u32 s98, s58, 0x11200000
	s_addc_u32 s99, s59, 0
	s_cmpk_lt_i32 s2, 0x400
	s_cselect_b64 s[4:5], -1, 0
	s_cmpk_gt_i32 s2, 0x3ff
	v_readfirstlane_b32 s6, v224
	s_waitcnt lgkmcnt(0)
	s_barrier
	s_cbranch_scc1 .LBB0_399
	s_ashr_i32 s0, s2, 31
	s_lshr_b32 s0, s0, 29
	s_add_i32 s7, s2, s0
	s_and_b32 s0, s7, -8
	s_sub_i32 s8, s2, s0
	s_cmp_gt_i32 s8, -1
	s_cbranch_scc0 .LBB0_396
	s_lshl_b32 s9, s8, 7
	s_cbranch_execz .LBB0_397
	s_branch .LBB0_398

; #define PG8_STAGE(bufoff, gbase, voff) do { _Pragma("unroll") for (int _i = 0; _i < 2; ++_i) \
;         __builtin_amdgcn_global_load_lds((const unsigned*)((const char*)(gbase) + (voff)[_i]), (PG8_LAS unsigned*)(lds + (bufoff) + ldsw + _i * 8192), 16, 0, 0); } while (0)
; #define PG8_WAIT_V(n) asm volatile("s_waitcnt vmcnt(" #n ")" ::: "memory")
; #define PG8_BAR __builtin_amdgcn_s_barrier()
; template <class Epi, class Sched, bool ALIGN_EPI = false, bool SP2 = false, bool F16 = false>
; __device__ __forceinline__ void gemm_phase(PG8_LAS unsigned char* lds, const Gemm g, const Sched& S, const Epi& E) {
;     ...
;     const char* cA = (const char*)g.A + (size_t)cur.pm * tstep; const char* cB = (const char*)g.Bt + (size_t)cur.pn * tstep;
;     S.a_ready(cur);
;     if constexpr (SP2) {
;         PG8_STAGE(PG8_SB(0, 0), cB, voffB); PG8_STAGE(PG8_SB(0, 1), cB + hstep, voffB); PG8_STAGE(PG8_SA(0, 0), cA, voffA); PG8_STAGE(PG8_SA(0, 1), cA + hstep, voffA);
;         if (wr == 1) PG8_BAR;
;         PG8_WAIT_V(2); PG8_BAR;
;         PG8_STAGE(PG8_SB(1, 0), cB + kstep, voffB); PG8_STAGE(PG8_SA(1, 0), cA + kstep, voffA); PG8_STAGE(PG8_SB(1, 1), cB + hstep + kstep, voffB);
;         PG8_WAIT_V(6); PG8_BAR;
.LBB0_399:
	v_bfe_u32 v202, v224, 4, 2
	v_lshlrev_b32_e32 v203, 4, v202
	s_add_u32 s10, s58, 0xc8000
	v_cndmask_b32_e64 v0, 0, 1, s[4:5]
	v_lshlrev_b32_e32 v161, 3, v202
	s_addc_u32 s11, s59, 0
	v_cmp_ne_u32_e64 s[0:1], 1, v0
	s_andn2_b64 vcc, exec, s[4:5]
	v_bitop3_b32 v204, v203, v240, v239 bitop3:0x36
	s_cbranch_vccnz .LBB0_435
	s_add_u32 s33, s58, 0xb00000
	s_addc_u32 s36, s59, 0
	s_lshr_b32 s5, s6, 6
	s_ashr_i32 s27, s26, 31
	s_ashr_i32 s25, s24, 31
	s_lshr_b32 s4, s6, 8
	s_lshl_b32 s37, s5, 10
	s_lshl_b64 s[8:9], s[26:27], 19
	s_lshl_b64 s[12:13], s[24:25], 19
	s_add_u32 s30, s33, s12
	s_addc_u32 s31, s36, s13
	s_add_i32 s27, s37, 0
	s_add_i32 m0, s27, 0x10000
	v_mov_b32_e32 v165, 0
	global_load_lds_dwordx4 v164, s[30:31]
	s_add_i32 m0, s27, 0x12000
	s_add_u32 s12, s30, 0x40000
	global_load_lds_dwordx4 v168, s[30:31]
	s_addc_u32 s13, s31, 0
	s_add_i32 m0, s27, 0x14000
	v_mov_b32_e32 v169, v165
	global_load_lds_dwordx4 v164, s[12:13]
	s_add_i32 m0, s27, 0x16000
	s_add_u32 s28, s98, s8
	s_addc_u32 s29, s99, s9
	s_add_i32 s38, s27, 0x2000
	global_load_lds_dwordx4 v168, s[12:13]
	s_mov_b32 m0, s27
	s_add_u32 s8, s28, 0x40000
	global_load_lds_dwordx4 v162, s[28:29]
	s_mov_b32 m0, s38
	s_addc_u32 s9, s29, 0
	s_add_i32 s39, s27, 0x4000
	global_load_lds_dwordx4 v166, s[28:29]
	s_mov_b32 m0, s39
	s_add_i32 s40, s27, 0x6000
	global_load_lds_dwordx4 v162, s[8:9]
	s_mov_b32 m0, s40
	v_mov_b32_e32 v163, v165
	global_load_lds_dwordx4 v166, s[8:9]
	v_mov_b32_e32 v167, v165
	s_cmp_eq_u32 s4, 1
	s_mov_b32 s41, 0
	v_lshl_add_u64 v[6:7], s[30:31], 0, v[164:165]
	v_lshl_add_u64 v[4:5], s[30:31], 0, v[168:169]
	v_lshl_add_u64 v[0:1], s[28:29], 0, v[162:163]
	s_cselect_b64 s[8:9], -1, 0
	s_cmp_lg_u32 s4, 1
	v_lshl_add_u64 v[2:3], s[28:29], 0, v[166:167]
	s_cbranch_scc1 .LBB0_402
	s_barrier

; template <class Epi, class Sched, bool ALIGN_EPI = false, bool SP2 = false, bool F16 = false>
; __device__ __forceinline__ void gemm_phase(PG8_LAS unsigned char* lds, const Gemm g, const Sched& S, const Epi& E) {
;     ...
;         const bool has_next = S.next(ui + 1, nxt);
;         const char* nA = has_next ? (const char*)g.A + (size_t)nxt.pm * tstep : cA; const char* nB = has_next ? (const char*)g.Bt + (size_t)nxt.pn * tstep : cB;
;         for (int t = 0; t < nt; t += 2) {
;             const bool last = (t == nt - 2);
;             const char* a1 = cA + (size_t)(t + 1) * kstep;
;             const char* a2 = last ? nA : cA + (size_t)(t + 2) * kstep; const char* b2 = last ? nB : cB + (size_t)(t + 2) * kstep;
;             const char* a3 = a2 + kstep; const char* b3 = b2 + kstep;
;     ...
; #pragma unroll
;         for (int a = 0; a < 2; ++a)
; #pragma unroll
;             for (int b = 0; b < 2; ++b)
; #pragma unroll
;                 for (int m = 0; m < 4; ++m)
; #pragma unroll
;                     for (int n = 0; n < 2; ++n) acc[a][b][m][n] = (f32x4){0.f, 0.f, 0.f, 0.f};
;         cur = nxt; cA = nA; cB = nB; ++ui;
.LBB0_411:
	s_ashr_i32 s19, s18, 31
	s_lshl_b64 s[20:21], s[18:19], 19
	s_add_u32 s20, s98, s20
	s_addc_u32 s21, s99, s21
	s_and_b64 s[22:23], s[6:7], exec
	s_cselect_b32 s19, s21, s29
	s_cselect_b32 s25, s20, s28
	s_ashr_i32 s17, s16, 31
	s_lshl_b64 s[22:23], s[16:17], 19
	s_add_u32 s22, s33, s22
	s_addc_u32 s23, s36, s23
	s_and_b64 s[34:35], s[6:7], exec
	s_cselect_b32 s17, s23, s31
	s_cselect_b32 s67, s22, s30
	s_add_u32 s28, s28, 0x40080
	s_addc_u32 s29, s29, 0
	s_add_u32 s68, s30, 0x100
	v_mov_b32_e32 v0, 0
	s_addc_u32 s69, s31, 0
	s_mov_b32 s70, -2
	v_mov_b32_e32 v1, v0
	v_mov_b32_e32 v2, v0
	s_waitcnt lgkmcnt(0)
	v_mov_b32_e32 v3, v0
	v_mov_b32_e32 v8, v0
	v_mov_b32_e32 v9, v0
	v_mov_b32_e32 v10, v0
	v_mov_b32_e32 v11, v0
	v_mov_b32_e32 v16, v0
	v_mov_b32_e32 v17, v0
	v_mov_b32_e32 v18, v0
	v_mov_b32_e32 v19, v0
	v_mov_b32_e32 v24, v0
	v_mov_b32_e32 v25, v0
	v_mov_b32_e32 v26, v0
	v_mov_b32_e32 v27, v0
	v_mov_b32_e32 v32, v0
	v_mov_b32_e32 v33, v0
	v_mov_b32_e32 v34, v0
	v_mov_b32_e32 v35, v0
	v_mov_b32_e32 v40, v0
	v_mov_b32_e32 v41, v0
	v_mov_b32_e32 v42, v0
	v_mov_b32_e32 v43, v0
	v_mov_b32_e32 v48, v0
	v_mov_b32_e32 v49, v0
	v_mov_b32_e32 v50, v0
	v_mov_b32_e32 v51, v0
	v_mov_b32_e32 v56, v0
	v_mov_b32_e32 v57, v0
	v_mov_b32_e32 v58, v0
	v_mov_b32_e32 v59, v0
	v_mov_b32_e32 v4, v0
	v_mov_b32_e32 v5, v0
	v_mov_b32_e32 v6, v0
	v_mov_b32_e32 v7, v0
	v_mov_b32_e32 v12, v0
	v_mov_b32_e32 v13, v0
	v_mov_b32_e32 v14, v0
	v_mov_b32_e32 v15, v0
	v_mov_b32_e32 v20, v0
	v_mov_b32_e32 v21, v0
	v_mov_b32_e32 v22, v0
	v_mov_b32_e32 v23, v0
	v_mov_b32_e32 v28, v0
	v_mov_b32_e32 v29, v0
	v_mov_b32_e32 v30, v0
	v_mov_b32_e32 v31, v0
	v_mov_b32_e32 v36, v0
	v_mov_b32_e32 v37, v0
	v_mov_b32_e32 v38, v0
	v_mov_b32_e32 v39, v0
	v_mov_b32_e32 v44, v0
	v_mov_b32_e32 v45, v0
	v_mov_b32_e32 v46, v0
	v_mov_b32_e32 v47, v0
	v_mov_b32_e32 v52, v0
	v_mov_b32_e32 v53, v0
	v_mov_b32_e32 v54, v0
	v_mov_b32_e32 v55, v0
	v_mov_b32_e32 v60, v0
	v_mov_b32_e32 v61, v0
	v_mov_b32_e32 v62, v0
	v_mov_b32_e32 v63, v0
	v_mov_b32_e32 v64, v0
	v_mov_b32_e32 v65, v0
	v_mov_b32_e32 v66, v0
	v_mov_b32_e32 v67, v0
	v_mov_b32_e32 v72, v0
	v_mov_b32_e32 v73, v0
	v_mov_b32_e32 v74, v0
	v_mov_b32_e32 v75, v0
	v_mov_b32_e32 v80, v0
	v_mov_b32_e32 v81, v0
	v_mov_b32_e32 v82, v0
	v_mov_b32_e32 v83, v0
	v_mov_b32_e32 v88, v0
	v_mov_b32_e32 v89, v0
	v_mov_b32_e32 v90, v0
	v_mov_b32_e32 v91, v0
	v_mov_b32_e32 v96, v0
	v_mov_b32_e32 v97, v0
	v_mov_b32_e32 v98, v0
	v_mov_b32_e32 v99, v0
	v_mov_b32_e32 v104, v0
	v_mov_b32_e32 v105, v0
	v_mov_b32_e32 v106, v0
	v_mov_b32_e32 v107, v0
	v_mov_b32_e32 v112, v0
	v_mov_b32_e32 v113, v0
	v_mov_b32_e32 v114, v0
	v_mov_b32_e32 v115, v0
	v_mov_b32_e32 v120, v0
	v_mov_b32_e32 v121, v0
	v_mov_b32_e32 v122, v0
	v_mov_b32_e32 v123, v0
	v_mov_b32_e32 v68, v0
	v_mov_b32_e32 v69, v0
	v_mov_b32_e32 v70, v0
	v_mov_b32_e32 v71, v0
	v_mov_b32_e32 v76, v0
	v_mov_b32_e32 v77, v0
	v_mov_b32_e32 v78, v0
	v_mov_b32_e32 v79, v0
	v_mov_b32_e32 v84, v0
	v_mov_b32_e32 v85, v0
	v_mov_b32_e32 v86, v0
	v_mov_b32_e32 v87, v0
	v_mov_b32_e32 v92, v0
	v_mov_b32_e32 v93, v0
	v_mov_b32_e32 v94, v0
	v_mov_b32_e32 v95, v0
	v_mov_b32_e32 v100, v0
	v_mov_b32_e32 v101, v0
	v_mov_b32_e32 v102, v0
	v_mov_b32_e32 v103, v0
	v_mov_b32_e32 v108, v0
	v_mov_b32_e32 v109, v0
	v_mov_b32_e32 v110, v0
	v_mov_b32_e32 v111, v0
	v_mov_b32_e32 v116, v0
	v_mov_b32_e32 v117, v0
	v_mov_b32_e32 v118, v0
	v_mov_b32_e32 v119, v0
	v_mov_b32_e32 v124, v0
	v_mov_b32_e32 v125, v0
	v_mov_b32_e32 v126, v0
	v_mov_b32_e32 v127, v0
